# mixer-A main loop: PV (first accumulator pair) MFMA snake order on top of QK snake
# speedup vs baseline: 1.0005x; 1.0002x over previous
.LBB0_276:
	s_mov_b32 s4, s92
	s_mov_b32 s6, s89
	v_cvt_pk_bf16_f32 v154, v90, v91
	v_lshl_add_u32 v210, s7, 1, v235
	ds_read_b64_tr_b16 v[68:69], v210 offset:24576
	ds_read_b64_tr_b16 v[70:71], v210 offset:25088
	v_add_f32_e32 v67, v98, v99
	v_add_f32_e32 v67, v100, v67
	v_add_f32_e32 v67, v101, v67
	v_add_f32_e32 v67, v102, v67
	v_add_f32_e32 v67, v103, v67
	v_cvt_pk_bf16_f32 v174, v98, v99
	v_cvt_pk_bf16_f32 v175, v100, v101
	s_waitcnt lgkmcnt(9)
	v_mfma_f32_32x32x16_bf16 v[130:145], v[206:209], v[166:169], 0
	ds_read_b64_tr_b16 v[72:73], v210 offset:28672
	ds_read_b64_tr_b16 v[74:75], v210 offset:29184
	v_add_f32_e32 v67, v104, v67
	v_add_f32_e32 v67, v105, v67
	v_add_f32_e32 v67, v106, v67
	v_add_f32_e32 v67, v107, v67
	v_cvt_pk_bf16_f32 v176, v102, v103
	v_cvt_pk_bf16_f32 v177, v104, v105
	s_waitcnt lgkmcnt(10)
	v_mfma_f32_32x32x16_bf16 v[114:129], v[198:201], v[166:169], 0
	ds_read_b64_tr_b16 v[76:77], v210 offset:25600
	ds_read_b64_tr_b16 v[78:79], v210 offset:26112
	v_add_f32_e32 v67, v108, v67
	v_add_f32_e32 v67, v109, v67
	v_add_f32_e32 v67, v110, v67
	v_add_f32_e32 v67, v111, v67
	v_cvt_pk_bf16_f32 v170, v106, v107
	v_cvt_pk_bf16_f32 v171, v108, v109
	s_waitcnt lgkmcnt(11)
	v_mfma_f32_32x32x16_bf16 v[114:129], v[194:197], v[158:161], v[114:129]
	ds_read_b64_tr_b16 v[98:99], v210 offset:29696
	ds_read_b64_tr_b16 v[100:101], v210 offset:30208
	v_add_f32_e32 v67, v112, v67
	v_add_f32_e32 v67, v113, v67
	v_add_f32_e32 v67, v82, v67
	v_add_f32_e32 v67, v83, v67
	v_cvt_pk_bf16_f32 v172, v110, v111
	v_cvt_pk_bf16_f32 v173, v112, v113
	s_waitcnt lgkmcnt(12)
	v_mfma_f32_32x32x16_bf16 v[130:145], v[202:205], v[158:161], v[130:145]
	ds_read_b64_tr_b16 v[102:103], v210 offset:26624
	ds_read_b64_tr_b16 v[104:105], v210 offset:27136
	v_add_f32_e32 v67, v84, v67
	v_add_f32_e32 v67, v85, v67
	v_add_f32_e32 v67, v86, v67
	v_add_f32_e32 v67, v87, v67
	v_cvt_pk_bf16_f32 v162, v82, v83
	v_cvt_pk_bf16_f32 v163, v84, v85
	s_waitcnt lgkmcnt(13)
	v_mfma_f32_32x32x16_bf16 v[130:145], v[190:193], v[150:153], v[130:145]
	ds_read_b64_tr_b16 v[106:107], v210 offset:30720
	ds_read_b64_tr_b16 v[108:109], v210 offset:31232
	v_add_f32_e32 v67, v88, v67
	v_add_f32_e32 v67, v89, v67
	v_add_f32_e32 v67, v90, v67
	v_add_f32_e32 v67, v91, v67
	v_cvt_pk_bf16_f32 v164, v86, v87
	v_cvt_pk_bf16_f32 v165, v88, v89
	s_waitcnt lgkmcnt(14)
	v_mfma_f32_32x32x16_bf16 v[114:129], v[186:189], v[150:153], v[114:129]
	ds_read_b64_tr_b16 v[110:111], v210 offset:27648
	ds_read_b64_tr_b16 v[112:113], v210 offset:28160
	v_add_f32_e32 v67, v92, v67
	v_add_f32_e32 v67, v93, v67
	v_add_f32_e32 v67, v94, v67
	v_add_f32_e32 v67, v95, v67
	s_waitcnt lgkmcnt(14)
	v_mfma_f32_32x32x16_bf16 v[114:129], v[178:181], v[146:149], v[114:129]
	ds_read_b64_tr_b16 v[188:189], v210 offset:31744
	ds_read_b64_tr_b16 v[190:191], v210 offset:32256
	v_add_f32_e32 v67, v96, v67
	v_add_f32_e32 v67, v97, v67
	v_add_f32_e32 v67, 0, v67
	v_mfma_f32_32x32x16_bf16 v[130:145], v[182:185], v[146:149], v[130:145]
	s_add_u32 s8, s2, 0xfffe0000
	s_addc_u32 s9, s3, -1
	s_add_i32 s7, s89, s86
	s_mov_b32 s10, m0
	s_mov_b32 m0, s7
	s_nop 0
	global_load_lds_dwordx4 v222, s[8:9]
	s_mov_b32 m0, s10
	s_add_u32 s8, s0, 0xfffe0000
	s_addc_u32 s9, s1, -1
	s_lshl_b32 s7, s92, 1
	s_add_i32 s7, s7, s87
	s_mov_b32 s10, m0
	s_mov_b32 m0, s7
	s_nop 0
	global_load_lds_dwordx4 v223, s[8:9]
	s_mov_b32 m0, s10
	s_add_u32 s8, s0, 0xfffe0080
	s_addc_u32 s9, s1, -1
	s_addk_i32 s7, 0x2000
	s_mov_b32 s10, m0
	s_mov_b32 m0, s7
	s_nop 0
	global_load_lds_dwordx4 v223, s[8:9]
	s_mov_b32 m0, s10
	v_add_f32_e32 v186, v66, v67
	s_waitcnt lgkmcnt(14)
	v_mfma_f32_32x32x16_bf16 v[2:17], v[174:177], v[68:71], v[2:17]
	v_exp_f32_e32 v130, v130
	ds_read_b64_tr_b16 v[192:193], v210 offset:32768
	ds_read_b64_tr_b16 v[194:195], v210 offset:33280
	s_waitcnt lgkmcnt(14)
	v_mfma_f32_32x32x16_bf16 v[18:33], v[174:177], v[72:75], v[18:33]
	v_exp_f32_e32 v131, v131
	v_cvt_pk_bf16_f32 v155, v92, v93
	ds_read_b64_tr_b16 v[90:91], v210 offset:36864
	ds_read_b64_tr_b16 v[92:93], v210 offset:37376
	v_add_u32_e32 v66, s4, v237
	ds_read_b128 v[86:89], v66
	ds_read_b128 v[82:85], v66 offset:512
	s_waitcnt lgkmcnt(14)
	v_mfma_f32_32x32x16_bf16 v[18:33], v[170:173], v[98:101], v[18:33]
	v_exp_f32_e32 v132, v132
	v_cvt_pk_bf16_f32 v156, v94, v95
	ds_read_b64_tr_b16 v[196:197], v210 offset:33792
	ds_read_b64_tr_b16 v[198:199], v210 offset:34304
	ds_read_b128 v[182:185], v66 offset:2048
	v_mfma_f32_32x32x16_bf16 v[2:17], v[170:173], v[76:79], v[2:17]
	ds_read_b128 v[78:81], v66 offset:2560
	v_exp_f32_e32 v133, v133
	v_cvt_pk_bf16_f32 v157, v96, v97
	ds_read_b64_tr_b16 v[94:95], v210 offset:37888
	ds_read_b64_tr_b16 v[96:97], v210 offset:38400
	ds_read_b128 v[178:181], v66 offset:4096
	ds_read_b128 v[74:77], v66 offset:4608
	s_waitcnt lgkmcnt(14)
	v_mfma_f32_32x32x16_bf16 v[2:17], v[162:165], v[102:105], v[2:17]
	v_exp_f32_e32 v134, v134
	ds_read_b64_tr_b16 v[98:99], v210 offset:34816
	ds_read_b64_tr_b16 v[100:101], v210 offset:35328
	ds_read_b128 v[70:73], v66 offset:6144
	ds_read_b128 v[66:69], v66 offset:6656
	v_mfma_f32_32x32x16_bf16 v[18:33], v[162:165], v[106:109], v[18:33]
	v_exp_f32_e32 v135, v135
	ds_read_b64_tr_b16 v[102:103], v210 offset:38912
	ds_read_b64_tr_b16 v[104:105], v210 offset:39424
	v_mfma_f32_32x32x16_bf16 v[18:33], v[154:157], v[188:191], v[18:33]
	v_exp_f32_e32 v136, v136
	ds_read_b64_tr_b16 v[106:107], v210 offset:35840
	ds_read_b64_tr_b16 v[108:109], v210 offset:36352
	v_mfma_f32_32x32x16_bf16 v[2:17], v[154:157], v[110:113], v[2:17]
	v_exp_f32_e32 v137, v137
	ds_read_b64_tr_b16 v[110:111], v210 offset:39936
	ds_read_b64_tr_b16 v[112:113], v210 offset:40448
	s_waitcnt lgkmcnt(14)
	v_mfma_f32_32x32x16_bf16 v[34:49], v[174:177], v[192:195], v[34:49]
	v_exp_f32_e32 v138, v138
	v_exp_f32_e32 v114, v114
	v_exp_f32_e32 v115, v115
	v_mfma_f32_32x32x16_bf16 v[50:65], v[174:177], v[90:93], v[50:65]
	v_exp_f32_e32 v139, v139
	v_exp_f32_e32 v116, v116
	v_exp_f32_e32 v117, v117
	v_mfma_f32_32x32x16_bf16 v[34:49], v[170:173], v[196:199], v[34:49]
	v_exp_f32_e32 v140, v140
	v_exp_f32_e32 v118, v118
	v_exp_f32_e32 v119, v119
	s_waitcnt lgkmcnt(12)
	v_mfma_f32_32x32x16_bf16 v[50:65], v[170:173], v[94:97], v[50:65]
	v_exp_f32_e32 v141, v141
	v_exp_f32_e32 v120, v120
	v_exp_f32_e32 v121, v121
	s_waitcnt lgkmcnt(8)
	v_mfma_f32_32x32x16_bf16 v[34:49], v[162:165], v[98:101], v[34:49]
	v_exp_f32_e32 v142, v142
	v_exp_f32_e32 v122, v122
	v_exp_f32_e32 v123, v123
	s_waitcnt lgkmcnt(4)
	v_mfma_f32_32x32x16_bf16 v[50:65], v[162:165], v[102:105], v[50:65]
	v_exp_f32_e32 v143, v143
	v_exp_f32_e32 v124, v124
	v_exp_f32_e32 v125, v125
	s_waitcnt lgkmcnt(2)
	v_mfma_f32_32x32x16_bf16 v[34:49], v[154:157], v[106:109], v[34:49]
	v_exp_f32_e32 v144, v144
	v_exp_f32_e32 v126, v126
	v_exp_f32_e32 v127, v127
	s_waitcnt lgkmcnt(0)
	v_mfma_f32_32x32x16_bf16 v[50:65], v[154:157], v[110:113], v[50:65]
	v_exp_f32_e32 v145, v145
	v_exp_f32_e32 v128, v128
	v_exp_f32_e32 v129, v129
	s_waitcnt vmcnt(3) lgkmcnt(0)
	s_barrier
	s_add_i32 s7, s92, 0x2000
	s_cmpk_lg_i32 s92, 0x4000
	s_cselect_b32 s89, s7, 0
	v_lshl_add_u32 v210, s6, 1, v235
	ds_read_b64_tr_b16 v[188:189], v210 offset:24576
	ds_read_b64_tr_b16 v[190:191], v210 offset:25088
	v_mfma_f32_32x32x16_bf16 v[98:113], v[86:89], v[166:169], 0
	v_add_f32_e32 v90, v130, v131
	v_add_f32_e32 v90, v132, v90
	v_add_f32_e32 v90, v133, v90
	v_add_f32_e32 v90, v134, v90
	v_add_f32_e32 v90, v135, v90
	v_cvt_pk_bf16_f32 v174, v130, v131
	v_cvt_pk_bf16_f32 v175, v132, v133
	ds_read_b64_tr_b16 v[130:131], v210 offset:28672
	ds_read_b64_tr_b16 v[132:133], v210 offset:29184
	v_add_f32_e32 v86, v136, v90
	v_add_f32_e32 v86, v137, v86
	v_add_f32_e32 v86, v138, v86
	v_add_f32_e32 v154, v139, v86
	v_mfma_f32_32x32x16_bf16 v[82:97], v[82:85], v[166:169], 0
	v_cvt_pk_bf16_f32 v176, v134, v135
	v_cvt_pk_bf16_f32 v177, v136, v137
	ds_read_b64_tr_b16 v[134:135], v210 offset:25600
	ds_read_b64_tr_b16 v[136:137], v210 offset:26112
	v_mfma_f32_32x32x16_bf16 v[82:97], v[78:81], v[158:161], v[82:97]
	v_add_f32_e32 v154, v140, v154
	v_add_f32_e32 v154, v141, v154
	v_add_f32_e32 v154, v142, v154
	v_add_f32_e32 v154, v143, v154
	v_cvt_pk_bf16_f32 v170, v138, v139
	v_cvt_pk_bf16_f32 v171, v140, v141
	ds_read_b64_tr_b16 v[138:139], v210 offset:29696
	ds_read_b64_tr_b16 v[140:141], v210 offset:30208
	v_mfma_f32_32x32x16_bf16 v[98:113], v[182:185], v[158:161], v[98:113]
	v_add_f32_e32 v78, v144, v154
	v_add_f32_e32 v78, v145, v78
	v_add_f32_e32 v78, v114, v78
	v_add_f32_e32 v154, v115, v78
	v_cvt_pk_bf16_f32 v172, v142, v143
	v_cvt_pk_bf16_f32 v173, v144, v145
	ds_read_b64_tr_b16 v[78:79], v210 offset:26624
	ds_read_b64_tr_b16 v[80:81], v210 offset:27136
	v_mfma_f32_32x32x16_bf16 v[98:113], v[178:181], v[150:153], v[98:113]
	v_add_f32_e32 v142, v116, v154
	v_add_f32_e32 v142, v117, v142
	v_add_f32_e32 v142, v118, v142
	v_add_f32_e32 v142, v119, v142
	v_cvt_pk_bf16_f32 v162, v114, v115
	v_cvt_pk_bf16_f32 v163, v116, v117
	ds_read_b64_tr_b16 v[114:115], v210 offset:30720
	ds_read_b64_tr_b16 v[116:117], v210 offset:31232
	v_mfma_f32_32x32x16_bf16 v[82:97], v[74:77], v[150:153], v[82:97]
	v_add_f32_e32 v74, v120, v142
	v_add_f32_e32 v74, v121, v74
	v_add_f32_e32 v74, v122, v74
	v_add_f32_e32 v142, v123, v74
	v_cvt_pk_bf16_f32 v164, v118, v119
	v_cvt_pk_bf16_f32 v165, v120, v121
	ds_read_b64_tr_b16 v[74:75], v210 offset:27648
	ds_read_b64_tr_b16 v[76:77], v210 offset:28160
	v_mfma_f32_32x32x16_bf16 v[82:97], v[66:69], v[146:149], v[82:97]
	v_add_f32_e32 v66, v124, v142
	v_add_f32_e32 v66, v125, v66
	v_add_f32_e32 v66, v126, v66
	v_add_f32_e32 v118, v127, v66
	v_mfma_f32_32x32x16_bf16 v[98:113], v[70:73], v[146:149], v[98:113]
	ds_read_b64_tr_b16 v[70:71], v210 offset:31744
	ds_read_b64_tr_b16 v[72:73], v210 offset:32256
	v_add_f32_e32 v66, v128, v118
	v_add_f32_e32 v66, v129, v66
	v_add_f32_e32 v66, 0, v66
	s_add_i32 s6, s92, s86
	s_mov_b32 s7, m0
	s_mov_b32 m0, s6
	s_nop 0
	global_load_lds_dwordx4 v222, s[2:3]
	s_mov_b32 m0, s7
	s_lshl_b32 s6, s89, 1
	s_add_i32 s76, s76, 2
	s_add_i32 s8, s6, s87
	s_mov_b32 s6, m0
	s_mov_b32 m0, s8
	s_nop 0
	global_load_lds_dwordx4 v223, s[0:1]
	s_mov_b32 m0, s6
	s_add_u32 s6, s0, 0x80
	s_addc_u32 s7, s1, 0
	s_addk_i32 s8, 0x2000
	s_mov_b32 s9, m0
	s_mov_b32 m0, s8
	s_nop 0
	global_load_lds_dwordx4 v223, s[6:7]
	s_mov_b32 m0, s9
	v_add_f32_e32 v66, v186, v66
	s_waitcnt lgkmcnt(14)
	v_mfma_f32_32x32x16_bf16 v[2:17], v[174:177], v[188:191], v[2:17]
	v_exp_f32_e32 v98, v98
	v_cvt_pk_bf16_f32 v154, v122, v123
	ds_read_b64_tr_b16 v[118:119], v210 offset:32768
	ds_read_b64_tr_b16 v[120:121], v210 offset:33280
	s_waitcnt lgkmcnt(14)
	v_mfma_f32_32x32x16_bf16 v[18:33], v[174:177], v[130:133], v[18:33]
	v_exp_f32_e32 v99, v99
	v_cvt_pk_bf16_f32 v155, v124, v125
	ds_read_b64_tr_b16 v[122:123], v210 offset:36864
	ds_read_b64_tr_b16 v[124:125], v210 offset:37376
	v_add_u32_e32 v67, s89, v237
	ds_read_b128 v[206:209], v67
	ds_read_b128 v[198:201], v67 offset:512
	s_waitcnt lgkmcnt(14)
	v_mfma_f32_32x32x16_bf16 v[18:33], v[170:173], v[138:141], v[18:33]
	v_exp_f32_e32 v100, v100
	v_cvt_pk_bf16_f32 v156, v126, v127
	ds_read_b64_tr_b16 v[130:131], v210 offset:33792
	ds_read_b64_tr_b16 v[132:133], v210 offset:34304
	ds_read_b128 v[202:205], v67 offset:2048
	ds_read_b128 v[194:197], v67 offset:2560
	v_mfma_f32_32x32x16_bf16 v[2:17], v[170:173], v[134:137], v[2:17]
	v_exp_f32_e32 v101, v101
	v_cvt_pk_bf16_f32 v157, v128, v129
	ds_read_b64_tr_b16 v[126:127], v210 offset:37888
	ds_read_b64_tr_b16 v[128:129], v210 offset:38400
	ds_read_b128 v[190:193], v67 offset:4096
	ds_read_b128 v[186:189], v67 offset:4608
	s_waitcnt lgkmcnt(14)
	v_mfma_f32_32x32x16_bf16 v[2:17], v[162:165], v[78:81], v[2:17]
	v_exp_f32_e32 v102, v102
	ds_read_b64_tr_b16 v[78:79], v210 offset:34816
	ds_read_b64_tr_b16 v[80:81], v210 offset:35328
	ds_read_b128 v[182:185], v67 offset:6144
	ds_read_b128 v[178:181], v67 offset:6656
	v_mfma_f32_32x32x16_bf16 v[18:33], v[162:165], v[114:117], v[18:33]
	v_exp_f32_e32 v103, v103
	ds_read_b64_tr_b16 v[114:115], v210 offset:38912
	ds_read_b64_tr_b16 v[116:117], v210 offset:39424
	v_mfma_f32_32x32x16_bf16 v[18:33], v[154:157], v[70:73], v[18:33]
	v_exp_f32_e32 v104, v104
	v_mfma_f32_32x32x16_bf16 v[2:17], v[154:157], v[74:77], v[2:17]
	ds_read_b64_tr_b16 v[74:75], v210 offset:35840
	ds_read_b64_tr_b16 v[76:77], v210 offset:36352
	v_exp_f32_e32 v105, v105
	ds_read_b64_tr_b16 v[68:69], v210 offset:39936
	ds_read_b64_tr_b16 v[70:71], v210 offset:40448
	s_waitcnt lgkmcnt(14)
	v_mfma_f32_32x32x16_bf16 v[34:49], v[174:177], v[118:121], v[34:49]
	v_exp_f32_e32 v106, v106
	v_exp_f32_e32 v82, v82
	v_exp_f32_e32 v83, v83
	v_mfma_f32_32x32x16_bf16 v[50:65], v[174:177], v[122:125], v[50:65]
	v_exp_f32_e32 v107, v107
	v_exp_f32_e32 v84, v84
	v_exp_f32_e32 v85, v85
	v_mfma_f32_32x32x16_bf16 v[34:49], v[170:173], v[130:133], v[34:49]
	v_exp_f32_e32 v108, v108
	v_exp_f32_e32 v86, v86
	v_exp_f32_e32 v87, v87
	s_waitcnt lgkmcnt(12)
	v_mfma_f32_32x32x16_bf16 v[50:65], v[170:173], v[126:129], v[50:65]
	v_exp_f32_e32 v109, v109
	v_exp_f32_e32 v88, v88
	v_exp_f32_e32 v89, v89
	s_waitcnt lgkmcnt(8)
	v_mfma_f32_32x32x16_bf16 v[34:49], v[162:165], v[78:81], v[34:49]
	v_exp_f32_e32 v110, v110
	v_exp_f32_e32 v90, v90
	v_exp_f32_e32 v91, v91
	s_waitcnt lgkmcnt(4)
	v_mfma_f32_32x32x16_bf16 v[50:65], v[162:165], v[114:117], v[50:65]
	v_exp_f32_e32 v111, v111
	v_exp_f32_e32 v92, v92
	v_exp_f32_e32 v93, v93
	s_waitcnt lgkmcnt(2)
	v_mfma_f32_32x32x16_bf16 v[34:49], v[154:157], v[74:77], v[34:49]
	v_exp_f32_e32 v112, v112
	v_exp_f32_e32 v94, v94
	v_exp_f32_e32 v95, v95
	s_waitcnt lgkmcnt(0)
	v_mfma_f32_32x32x16_bf16 v[50:65], v[154:157], v[68:71], v[50:65]
	v_exp_f32_e32 v113, v113
	v_exp_f32_e32 v96, v96
	v_exp_f32_e32 v97, v97
	s_add_i32 s6, s89, 0x2000
	s_cmpk_lg_i32 s89, 0x4000
	s_cselect_b32 s92, s6, 0
	s_add_u32 s0, s0, 0x40000
	s_addc_u32 s1, s1, 0
	s_waitcnt vmcnt(3) lgkmcnt(0)
	s_barrier
	s_add_u32 s2, s2, 0x40000
	s_addc_u32 s3, s3, 0
	s_cmp_ge_i32 s76, s5
	s_mov_b32 s7, s4
	s_cbranch_scc0 .LBB0_276
	s_branch .LBB0_278
